# NA item prologue loads batched; retention scan: fragment batches read back to back, q/k rescale as interleaved streams without s_nop
# baseline (speedup 1.0000x reference)
.LBB0_456:
	ds_write_b32 v178, v207
	s_or_b64 exec, exec, s[34:35]
	s_waitcnt vmcnt(7)
	v_lshlrev_b32_e32 v68, 16, v64
	v_and_b32_e32 v69, 0xffff0000, v64
	v_lshlrev_b32_e32 v250, 16, v65
	v_and_b32_e32 v251, 0xffff0000, v65
	v_lshlrev_b32_e32 v252, 16, v66
	v_and_b32_e32 v253, 0xffff0000, v66
	v_pk_mul_f32 v[68:69], v[152:153], v[68:69]
	v_pk_mul_f32 v[250:251], v[152:153], v[250:251]
	v_pk_mul_f32 v[252:253], v[152:153], v[252:253]
	v_cvt_pk_bf16_f32 v64, v68, v69
	v_lshlrev_b32_e32 v68, 16, v67
	v_and_b32_e32 v69, 0xffff0000, v67
	v_cvt_pk_bf16_f32 v65, v250, v251
	v_pk_mul_f32 v[68:69], v[152:153], v[68:69]
	v_cvt_pk_bf16_f32 v66, v252, v253
	v_cvt_pk_bf16_f32 v67, v68, v69
	s_waitcnt vmcnt(6)
	v_lshlrev_b32_e32 v68, 16, v60
	v_and_b32_e32 v69, 0xffff0000, v60
	v_lshlrev_b32_e32 v250, 16, v61
	v_and_b32_e32 v251, 0xffff0000, v61
	v_lshlrev_b32_e32 v252, 16, v62
	v_and_b32_e32 v253, 0xffff0000, v62
	v_pk_mul_f32 v[68:69], v[150:151], v[68:69]
	v_pk_mul_f32 v[250:251], v[150:151], v[250:251]
	v_pk_mul_f32 v[252:253], v[150:151], v[252:253]
	v_cvt_pk_bf16_f32 v60, v68, v69
	v_lshlrev_b32_e32 v68, 16, v63
	v_and_b32_e32 v69, 0xffff0000, v63
	v_cvt_pk_bf16_f32 v61, v250, v251
	v_pk_mul_f32 v[68:69], v[150:151], v[68:69]
	v_cvt_pk_bf16_f32 v62, v252, v253
	v_cvt_pk_bf16_f32 v63, v68, v69
	ds_write_b128 v118, v[64:67]
	ds_write_b128 v118, v[60:63] offset:33792
	s_waitcnt vmcnt(5)
	v_lshlrev_b32_e32 v60, 16, v56
	v_and_b32_e32 v61, 0xffff0000, v56
	v_lshlrev_b32_e32 v250, 16, v57
	v_and_b32_e32 v251, 0xffff0000, v57
	v_lshlrev_b32_e32 v252, 16, v58
	v_and_b32_e32 v253, 0xffff0000, v58
	v_pk_mul_f32 v[60:61], v[142:143], v[60:61]
	v_pk_mul_f32 v[250:251], v[142:143], v[250:251]
	v_pk_mul_f32 v[252:253], v[142:143], v[252:253]
	v_cvt_pk_bf16_f32 v56, v60, v61
	v_lshlrev_b32_e32 v60, 16, v59
	v_and_b32_e32 v61, 0xffff0000, v59
	v_cvt_pk_bf16_f32 v57, v250, v251
	v_pk_mul_f32 v[60:61], v[142:143], v[60:61]
	v_cvt_pk_bf16_f32 v58, v252, v253
	v_cvt_pk_bf16_f32 v59, v60, v61
	s_waitcnt vmcnt(4)
	v_lshlrev_b32_e32 v60, 16, v52
	v_and_b32_e32 v61, 0xffff0000, v52
	v_lshlrev_b32_e32 v250, 16, v53
	v_and_b32_e32 v251, 0xffff0000, v53
	v_lshlrev_b32_e32 v252, 16, v54
	v_and_b32_e32 v253, 0xffff0000, v54
	v_pk_mul_f32 v[60:61], v[140:141], v[60:61]
	v_pk_mul_f32 v[250:251], v[140:141], v[250:251]
	v_pk_mul_f32 v[252:253], v[140:141], v[252:253]
	v_cvt_pk_bf16_f32 v52, v60, v61
	v_lshlrev_b32_e32 v60, 16, v55
	v_and_b32_e32 v61, 0xffff0000, v55
	v_cvt_pk_bf16_f32 v53, v250, v251
	v_pk_mul_f32 v[60:61], v[140:141], v[60:61]
	v_cvt_pk_bf16_f32 v54, v252, v253
	v_cvt_pk_bf16_f32 v55, v60, v61
	ds_write_b128 v120, v[56:59]
	ds_write_b128 v120, v[52:55] offset:33792
	s_waitcnt vmcnt(3)
	v_lshlrev_b32_e32 v52, 16, v48
	v_and_b32_e32 v53, 0xffff0000, v48
	v_lshlrev_b32_e32 v250, 16, v49
	v_and_b32_e32 v251, 0xffff0000, v49
	v_lshlrev_b32_e32 v252, 16, v50
	v_and_b32_e32 v253, 0xffff0000, v50
	v_pk_mul_f32 v[52:53], v[138:139], v[52:53]
	v_pk_mul_f32 v[250:251], v[138:139], v[250:251]
	v_pk_mul_f32 v[252:253], v[138:139], v[252:253]
	v_cvt_pk_bf16_f32 v48, v52, v53
	v_lshlrev_b32_e32 v52, 16, v51
	v_and_b32_e32 v53, 0xffff0000, v51
	v_cvt_pk_bf16_f32 v49, v250, v251
	v_pk_mul_f32 v[52:53], v[138:139], v[52:53]
	v_cvt_pk_bf16_f32 v50, v252, v253
	v_cvt_pk_bf16_f32 v51, v52, v53
	s_waitcnt vmcnt(2)
	v_lshlrev_b32_e32 v52, 16, v44
	v_and_b32_e32 v53, 0xffff0000, v44
	v_lshlrev_b32_e32 v250, 16, v45
	v_and_b32_e32 v251, 0xffff0000, v45
	v_lshlrev_b32_e32 v252, 16, v46
	v_and_b32_e32 v253, 0xffff0000, v46
	v_pk_mul_f32 v[52:53], v[136:137], v[52:53]
	v_pk_mul_f32 v[250:251], v[136:137], v[250:251]
	v_pk_mul_f32 v[252:253], v[136:137], v[252:253]
	v_cvt_pk_bf16_f32 v44, v52, v53
	v_lshlrev_b32_e32 v52, 16, v47
	v_and_b32_e32 v53, 0xffff0000, v47
	v_cvt_pk_bf16_f32 v45, v250, v251
	v_pk_mul_f32 v[52:53], v[136:137], v[52:53]
	v_cvt_pk_bf16_f32 v46, v252, v253
	v_cvt_pk_bf16_f32 v47, v52, v53
	ds_write_b128 v122, v[48:51]
	ds_write_b128 v122, v[44:47] offset:33792
	s_waitcnt vmcnt(1)
	v_lshlrev_b32_e32 v44, 16, v40
	v_and_b32_e32 v45, 0xffff0000, v40
	v_lshlrev_b32_e32 v250, 16, v41
	v_and_b32_e32 v251, 0xffff0000, v41
	v_lshlrev_b32_e32 v252, 16, v42
	v_and_b32_e32 v253, 0xffff0000, v42
	v_pk_mul_f32 v[44:45], v[134:135], v[44:45]
	v_pk_mul_f32 v[250:251], v[134:135], v[250:251]
	v_pk_mul_f32 v[252:253], v[134:135], v[252:253]
	v_cvt_pk_bf16_f32 v40, v44, v45
	v_lshlrev_b32_e32 v44, 16, v43
	v_and_b32_e32 v45, 0xffff0000, v43
	v_cvt_pk_bf16_f32 v41, v250, v251
	v_pk_mul_f32 v[44:45], v[134:135], v[44:45]
	v_cvt_pk_bf16_f32 v42, v252, v253
	v_cvt_pk_bf16_f32 v43, v44, v45
	s_waitcnt vmcnt(0)
	v_lshlrev_b32_e32 v44, 16, v36
	v_and_b32_e32 v45, 0xffff0000, v36
	v_lshlrev_b32_e32 v250, 16, v37
	v_and_b32_e32 v251, 0xffff0000, v37
	v_lshlrev_b32_e32 v252, 16, v38
	v_and_b32_e32 v253, 0xffff0000, v38
	v_pk_mul_f32 v[44:45], v[132:133], v[44:45]
	v_pk_mul_f32 v[250:251], v[132:133], v[250:251]
	v_pk_mul_f32 v[252:253], v[132:133], v[252:253]
	v_cvt_pk_bf16_f32 v36, v44, v45
	v_lshlrev_b32_e32 v44, 16, v39
	v_and_b32_e32 v45, 0xffff0000, v39
	v_cvt_pk_bf16_f32 v37, v250, v251
	v_pk_mul_f32 v[44:45], v[132:133], v[44:45]
	v_cvt_pk_bf16_f32 v38, v252, v253
	v_cvt_pk_bf16_f32 v39, v44, v45
	ds_write_b128 v124, v[40:43]
	ds_write_b128 v124, v[36:39] offset:33792
	s_and_saveexec_b64 s[34:35], s[4:5]
	s_cbranch_execz .LBB0_459
	v_add_u32_e32 v36, v175, v179
	ds_write_b16 v36, v0
	ds_write_b16_d16_hi v36, v0 offset:144
	ds_write_b16 v36, v1 offset:288
	ds_write_b16_d16_hi v36, v1 offset:432
	ds_write_b16 v36, v2 offset:576
	ds_write_b16_d16_hi v36, v2 offset:720
	ds_write_b16 v36, v3 offset:864
	ds_write_b16_d16_hi v36, v3 offset:1008

.LBB0_495:
	s_or_b64 exec, exec, s[36:37]
	s_waitcnt lgkmcnt(8)
	s_nop 5
	v_cndmask_b32_e64 v68, v100, 0, s[22:23]
	v_cndmask_b32_e64 v69, 0, v101, s[24:25]
	v_cndmask_b32_e64 v68, v68, v100, s[24:25]
	v_cndmask_b32_e64 v70, v102, 0, s[26:27]
	v_cndmask_b32_e64 v71, v103, 0, s[28:29]
	v_cvt_pk_bf16_f32 v68, v68, v69
	v_cvt_pk_bf16_f32 v69, v70, v71
	ds_write_b64 v182, v[68:69] offset:32
	s_waitcnt lgkmcnt(0)
	s_barrier
	ds_read_b128 v[84:87], v203 offset:64
	ds_read_b128 v[92:95], v203
	ds_read_b128 v[68:71], v204 offset:448
	ds_read_b128 v[72:75], v204 offset:384
	ds_read_b128 v[76:79], v204 offset:320
	ds_read_b128 v[80:83], v204 offset:256
	ds_read_b128 v[88:91], v204 offset:192
	ds_read_b128 v[96:99], v204 offset:128
	ds_read_b128 v[100:103], v204 offset:64
	ds_read_b128 v[104:107], v204
	ds_read_b128 v[108:111], v205 offset:64
	ds_read_b128 v[214:217], v205
	ds_read_b128 v[218:221], v201 offset:448
	ds_read_b128 v[222:225], v201 offset:384
	ds_read_b128 v[226:229], v201 offset:320
	ds_read_b128 v[230:233], v201 offset:256
	ds_read_b128 v[234:237], v201 offset:192
	ds_read_b128 v[238:241], v201 offset:128
	ds_read_b128 v[242:245], v201 offset:64
	ds_read_b128 v[246:249], v201
	s_waitcnt lgkmcnt(0)
	v_mfma_f32_16x16x32_bf16 v[214:217], v[92:95], v[214:217], 0
	s_cmp_lt_u32 s56, 4
	s_cselect_b64 s[36:37], -1, 0
	s_cmp_gt_u32 s56, 3
	v_mfma_f32_16x16x32_bf16 v[108:111], v[84:87], v[108:111], v[214:217]
	s_cselect_b64 s[74:75], -1, 0
	s_lshl_b32 s56, s56, 6
	s_and_b64 vcc, exec, s[34:35]
	v_mfma_f32_16x16x32_bf16 v[108:111], v[104:107], v[246:249], v[108:111]
	v_or_b32_e32 v213, s56, v125
	v_mfma_f32_16x16x32_bf16 v[108:111], v[100:103], v[242:245], v[108:111]
	v_mfma_f32_16x16x32_bf16 v[108:111], v[96:99], v[238:241], v[108:111]
	v_mfma_f32_16x16x32_bf16 v[108:111], v[88:91], v[234:237], v[108:111]
	v_mfma_f32_16x16x32_bf16 v[108:111], v[80:83], v[230:233], v[108:111]
	v_mfma_f32_16x16x32_bf16 v[108:111], v[76:79], v[226:229], v[108:111]
	v_mfma_f32_16x16x32_bf16 v[108:111], v[72:75], v[222:225], v[108:111]
	v_mfma_f32_16x16x32_bf16 v[108:111], v[68:71], v[218:221], v[108:111]
	s_cbranch_vccnz .LBB0_501
	s_mov_b64 s[72:73], -1
	s_and_b64 vcc, exec, s[74:75]
	s_cbranch_vccz .LBB0_498
	v_add_u32_e32 v214, 16, v208
	s_mov_b64 s[72:73], 0

.LBB0_505:
	v_cmp_gt_i32_e32 vcc, s2, v72
	v_add_u32_e32 v74, 0xffffff00, v72
	v_ashrrev_i32_e32 v73, 31, v72
	v_cndmask_b32_e32 v72, v74, v72, vcc
	v_mov_b32_e32 v74, s9
	v_mov_b32_e32 v75, s39
	v_cndmask_b32_e32 v73, 0, v73, vcc
	v_cndmask_b32_e32 v75, v74, v75, vcc
	v_mov_b32_e32 v74, s8
	v_mov_b32_e32 v76, s38
	v_cndmask_b32_e32 v74, v74, v76, vcc
	v_lshlrev_b64 v[72:73], 12, v[72:73]
	v_lshl_add_u64 v[72:73], v[74:75], 0, v[72:73]
	v_lshl_add_u64 v[72:73], v[116:117], 1, v[72:73]
	v_lshl_add_u64 v[72:73], v[72:73], 0, v[112:113]
	v_cvt_pk_bf16_f32 v68, v68, v69
	v_cvt_pk_bf16_f32 v69, v70, v71
	global_store_dwordx2 v[72:73], v[68:69], off
	ds_read_b128 v[96:99], v193
	ds_read_b128 v[80:83], v193 offset:64
	ds_read_b128 v[92:95], v193 offset:2304
	ds_read_b128 v[76:79], v193 offset:2368
	ds_read_b128 v[88:91], v193 offset:4608
	ds_read_b128 v[68:71], v193 offset:4672
	ds_read_b128 v[84:87], v193 offset:6912
	ds_read_b128 v[72:75], v193 offset:6976
	ds_read_b64_tr_b16 v[100:101], v196 offset:33792
	ds_read_b64_tr_b16 v[102:103], v196 offset:35904
	ds_read_b64_tr_b16 v[104:105], v196 offset:50688
	ds_read_b64_tr_b16 v[106:107], v196 offset:52800
	s_add_i32 s54, s54, 64
	s_waitcnt lgkmcnt(2)
	v_mfma_f32_16x16x32_bf16 v[12:15], v[100:103], v[96:99], v[12:15]
	v_subrev_u32_e32 v208, 64, v208
	s_cmpk_eq_i32 s54, 0x20c0
	v_mfma_f32_16x16x32_bf16 v[16:19], v[100:103], v[92:95], v[16:19]
	v_mfma_f32_16x16x32_bf16 v[8:11], v[100:103], v[88:91], v[8:11]
	v_mfma_f32_16x16x32_bf16 v[4:7], v[100:103], v[84:87], v[4:7]
	ds_read_b128 v[100:103], v197
	s_waitcnt lgkmcnt(1)
	v_mfma_f32_16x16x32_bf16 v[12:15], v[104:107], v[80:83], v[12:15]
	v_mfma_f32_16x16x32_bf16 v[16:19], v[104:107], v[76:79], v[16:19]
	v_mfma_f32_16x16x32_bf16 v[8:11], v[104:107], v[68:71], v[8:11]
	s_waitcnt lgkmcnt(0)
	s_nop 4
	v_pk_mul_f32 v[14:15], v[14:15], v[102:103]
	v_pk_mul_f32 v[12:13], v[12:13], v[100:101]
	v_pk_mul_f32 v[18:19], v[18:19], v[102:103]
	v_mfma_f32_16x16x32_bf16 v[4:7], v[104:107], v[72:75], v[4:7]
	v_mul_f32_e64 v16, v16, v100
	v_mul_f32_e64 v17, v17, v101
	v_pk_mul_f32 v[10:11], v[10:11], v[102:103]
	v_pk_mul_f32 v[8:9], v[8:9], v[100:101]
	s_nop 3
	v_pk_mul_f32 v[6:7], v[6:7], v[102:103]
	v_pk_mul_f32 v[4:5], v[4:5], v[100:101]
	ds_read_b64_tr_b16 v[100:101], v196 offset:33824
	ds_read_b64_tr_b16 v[102:103], v196 offset:35936
	ds_read_b64_tr_b16 v[104:105], v196 offset:50720
	ds_read_b64_tr_b16 v[106:107], v196 offset:52832
	s_waitcnt lgkmcnt(2)
	v_mfma_f32_16x16x32_bf16 v[24:27], v[100:103], v[88:91], v[24:27]
	v_mfma_f32_16x16x32_bf16 v[32:35], v[100:103], v[96:99], v[32:35]
	v_mfma_f32_16x16x32_bf16 v[28:31], v[100:103], v[92:95], v[28:31]
	v_mfma_f32_16x16x32_bf16 v[20:23], v[100:103], v[84:87], v[20:23]
	s_waitcnt lgkmcnt(0)
	v_mfma_f32_16x16x32_bf16 v[24:27], v[104:107], v[68:71], v[24:27]
	ds_read_b128 v[68:71], v199
	s_waitcnt lgkmcnt(0)
	s_barrier
	v_mfma_f32_16x16x32_bf16 v[32:35], v[104:107], v[80:83], v[32:35]
	s_nop 3
	v_mul_f32_e64 v26, v26, v70
	v_mul_f32_e64 v27, v27, v71
	v_pk_mul_f32 v[24:25], v[24:25], v[68:69]
	v_mfma_f32_16x16x32_bf16 v[28:31], v[104:107], v[76:79], v[28:31]
	v_mfma_f32_16x16x32_bf16 v[20:23], v[104:107], v[72:75], v[20:23]
	v_mul_f32_e64 v34, v34, v70
	v_mul_f32_e64 v35, v35, v71
	v_pk_mul_f32 v[32:33], v[32:33], v[68:69]
	s_nop 3
	v_pk_mul_f32 v[30:31], v[30:31], v[70:71]
	v_pk_mul_f32 v[28:29], v[28:29], v[68:69]
	v_pk_mul_f32 v[22:23], v[22:23], v[70:71]
	v_pk_mul_f32 v[20:21], v[20:21], v[68:69]
	s_cbranch_scc0 .LBB0_455
	s_and_saveexec_b64 s[34:35], s[6:7]
	ds_write_b32 v178, v207
	s_or_b64 exec, exec, s[34:35]
	s_waitcnt vmcnt(9)
	v_lshlrev_b32_e32 v68, 16, v64
	v_and_b32_e32 v69, 0xffff0000, v64
	v_lshlrev_b32_e32 v250, 16, v65
	v_and_b32_e32 v251, 0xffff0000, v65
	v_lshlrev_b32_e32 v252, 16, v66
	v_and_b32_e32 v253, 0xffff0000, v66
	v_pk_mul_f32 v[68:69], v[152:153], v[68:69]
	v_pk_mul_f32 v[250:251], v[152:153], v[250:251]
	v_pk_mul_f32 v[252:253], v[152:153], v[252:253]
	v_cvt_pk_bf16_f32 v64, v68, v69
	v_lshlrev_b32_e32 v68, 16, v67
	v_and_b32_e32 v69, 0xffff0000, v67
	v_cvt_pk_bf16_f32 v65, v250, v251
	v_pk_mul_f32 v[68:69], v[152:153], v[68:69]
	v_cvt_pk_bf16_f32 v66, v252, v253
	v_cvt_pk_bf16_f32 v67, v68, v69
	s_waitcnt vmcnt(8)
	v_lshlrev_b32_e32 v68, 16, v60
	v_and_b32_e32 v69, 0xffff0000, v60
	v_lshlrev_b32_e32 v250, 16, v61
	v_and_b32_e32 v251, 0xffff0000, v61
	v_lshlrev_b32_e32 v252, 16, v62
	v_and_b32_e32 v253, 0xffff0000, v62
	v_pk_mul_f32 v[68:69], v[150:151], v[68:69]
	v_pk_mul_f32 v[250:251], v[150:151], v[250:251]
	v_pk_mul_f32 v[252:253], v[150:151], v[252:253]
	v_cvt_pk_bf16_f32 v60, v68, v69
	v_lshlrev_b32_e32 v68, 16, v63
	v_and_b32_e32 v69, 0xffff0000, v63
	v_cvt_pk_bf16_f32 v61, v250, v251
	v_pk_mul_f32 v[68:69], v[150:151], v[68:69]
	v_cvt_pk_bf16_f32 v62, v252, v253
	v_cvt_pk_bf16_f32 v63, v68, v69
	ds_write_b128 v118, v[64:67]
	ds_write_b128 v118, v[60:63] offset:33792
	s_waitcnt vmcnt(7)
	v_lshlrev_b32_e32 v60, 16, v56
	v_and_b32_e32 v61, 0xffff0000, v56
	v_lshlrev_b32_e32 v250, 16, v57
	v_and_b32_e32 v251, 0xffff0000, v57
	v_lshlrev_b32_e32 v252, 16, v58
	v_and_b32_e32 v253, 0xffff0000, v58
	v_pk_mul_f32 v[60:61], v[142:143], v[60:61]
	v_pk_mul_f32 v[250:251], v[142:143], v[250:251]
	v_pk_mul_f32 v[252:253], v[142:143], v[252:253]
	v_cvt_pk_bf16_f32 v56, v60, v61
	v_lshlrev_b32_e32 v60, 16, v59
	v_and_b32_e32 v61, 0xffff0000, v59
	v_cvt_pk_bf16_f32 v57, v250, v251
	v_pk_mul_f32 v[60:61], v[142:143], v[60:61]
	v_cvt_pk_bf16_f32 v58, v252, v253
	v_cvt_pk_bf16_f32 v59, v60, v61
	s_waitcnt vmcnt(6)
	v_lshlrev_b32_e32 v60, 16, v52
	v_and_b32_e32 v61, 0xffff0000, v52
	v_lshlrev_b32_e32 v250, 16, v53
	v_and_b32_e32 v251, 0xffff0000, v53
	v_lshlrev_b32_e32 v252, 16, v54
	v_and_b32_e32 v253, 0xffff0000, v54
	v_pk_mul_f32 v[60:61], v[140:141], v[60:61]
	v_pk_mul_f32 v[250:251], v[140:141], v[250:251]
	v_pk_mul_f32 v[252:253], v[140:141], v[252:253]
	v_cvt_pk_bf16_f32 v52, v60, v61
	v_lshlrev_b32_e32 v60, 16, v55
	v_and_b32_e32 v61, 0xffff0000, v55
	v_cvt_pk_bf16_f32 v53, v250, v251
	v_pk_mul_f32 v[60:61], v[140:141], v[60:61]
	v_cvt_pk_bf16_f32 v54, v252, v253
	v_cvt_pk_bf16_f32 v55, v60, v61
	ds_write_b128 v120, v[56:59]
	ds_write_b128 v120, v[52:55] offset:33792
	s_waitcnt vmcnt(5)
	v_lshlrev_b32_e32 v52, 16, v48
	v_and_b32_e32 v53, 0xffff0000, v48
	v_lshlrev_b32_e32 v250, 16, v49
	v_and_b32_e32 v251, 0xffff0000, v49
	v_lshlrev_b32_e32 v252, 16, v50
	v_and_b32_e32 v253, 0xffff0000, v50
	v_pk_mul_f32 v[52:53], v[138:139], v[52:53]
	v_pk_mul_f32 v[250:251], v[138:139], v[250:251]
	v_pk_mul_f32 v[252:253], v[138:139], v[252:253]
	v_cvt_pk_bf16_f32 v48, v52, v53
	v_lshlrev_b32_e32 v52, 16, v51
	v_and_b32_e32 v53, 0xffff0000, v51
	v_cvt_pk_bf16_f32 v49, v250, v251
	v_pk_mul_f32 v[52:53], v[138:139], v[52:53]
	v_cvt_pk_bf16_f32 v50, v252, v253
	v_cvt_pk_bf16_f32 v51, v52, v53
	s_waitcnt vmcnt(4)
	v_lshlrev_b32_e32 v52, 16, v44
	v_and_b32_e32 v53, 0xffff0000, v44
	v_lshlrev_b32_e32 v250, 16, v45
	v_and_b32_e32 v251, 0xffff0000, v45
	v_lshlrev_b32_e32 v252, 16, v46
	v_and_b32_e32 v253, 0xffff0000, v46
	v_pk_mul_f32 v[52:53], v[136:137], v[52:53]
	v_pk_mul_f32 v[250:251], v[136:137], v[250:251]
	v_pk_mul_f32 v[252:253], v[136:137], v[252:253]
	v_cvt_pk_bf16_f32 v44, v52, v53
	v_lshlrev_b32_e32 v52, 16, v47
	v_and_b32_e32 v53, 0xffff0000, v47
	v_cvt_pk_bf16_f32 v45, v250, v251
	v_pk_mul_f32 v[52:53], v[136:137], v[52:53]
	v_cvt_pk_bf16_f32 v46, v252, v253
	v_cvt_pk_bf16_f32 v47, v52, v53
	ds_write_b128 v122, v[48:51]
	ds_write_b128 v122, v[44:47] offset:33792
	s_waitcnt vmcnt(3)
	v_lshlrev_b32_e32 v44, 16, v40
	v_and_b32_e32 v45, 0xffff0000, v40
	v_lshlrev_b32_e32 v250, 16, v41
	v_and_b32_e32 v251, 0xffff0000, v41
	v_lshlrev_b32_e32 v252, 16, v42
	v_and_b32_e32 v253, 0xffff0000, v42
	v_pk_mul_f32 v[44:45], v[134:135], v[44:45]
	v_pk_mul_f32 v[250:251], v[134:135], v[250:251]
	v_pk_mul_f32 v[252:253], v[134:135], v[252:253]
	v_cvt_pk_bf16_f32 v40, v44, v45
	v_lshlrev_b32_e32 v44, 16, v43
	v_and_b32_e32 v45, 0xffff0000, v43
	v_cvt_pk_bf16_f32 v41, v250, v251
	v_pk_mul_f32 v[44:45], v[134:135], v[44:45]
	v_cvt_pk_bf16_f32 v42, v252, v253
	v_cvt_pk_bf16_f32 v43, v44, v45
	s_waitcnt vmcnt(2)
	v_lshlrev_b32_e32 v44, 16, v36
	v_and_b32_e32 v45, 0xffff0000, v36
	v_lshlrev_b32_e32 v250, 16, v37
	v_and_b32_e32 v251, 0xffff0000, v37
	v_lshlrev_b32_e32 v252, 16, v38
	v_and_b32_e32 v253, 0xffff0000, v38
	v_pk_mul_f32 v[44:45], v[132:133], v[44:45]
	v_pk_mul_f32 v[250:251], v[132:133], v[250:251]
	v_pk_mul_f32 v[252:253], v[132:133], v[252:253]
	v_cvt_pk_bf16_f32 v36, v44, v45
	v_lshlrev_b32_e32 v44, 16, v39
	v_and_b32_e32 v45, 0xffff0000, v39
	v_cvt_pk_bf16_f32 v37, v250, v251
	v_pk_mul_f32 v[44:45], v[132:133], v[44:45]
	v_cvt_pk_bf16_f32 v38, v252, v253
	v_cvt_pk_bf16_f32 v39, v44, v45
	ds_write_b128 v124, v[40:43]
	ds_write_b128 v124, v[36:39] offset:33792
	s_and_saveexec_b64 s[34:35], s[4:5]
	s_cbranch_execz .LBB0_510
	v_add_u32_e32 v36, v175, v179
	ds_write_b16 v36, v0
	ds_write_b16_d16_hi v36, v0 offset:144
	ds_write_b16 v36, v1 offset:288
	ds_write_b16_d16_hi v36, v1 offset:432
	ds_write_b16 v36, v2 offset:576
	ds_write_b16_d16_hi v36, v2 offset:720
	ds_write_b16 v36, v3 offset:864
	ds_write_b16_d16_hi v36, v3 offset:1008

.LBB0_1562:
	s_ashr_i32 s7, s33, 6
	s_bfe_u32 s6, s33, 0x40002
	s_mul_hi_i32 s43, s7, 0x2100
	s_mul_i32 s42, s7, 0x2100
	s_lshl_b32 s14, s6, 7
	v_mov_b32_e32 v1, s43
	v_or_b32_e32 v0, s42, v154
	v_lshl_add_u64 v[4:5], v[82:83], 0, s[14:15]
	v_lshlrev_b64 v[0:1], 11, v[0:1]
	v_lshl_add_u64 v[0:1], v[4:5], 0, v[0:1]
	s_barrier
	global_load_dwordx4 v[8:11], v[0:1], off
	s_lshl_b32 s0, s7, 4
	s_or_b32 s0, s0, s6
	s_ashr_i32 s1, s0, 31
	v_mov_b32_e32 v1, s43
	v_or_b32_e32 v0, s42, v86
	v_lshlrev_b64 v[0:1], 11, v[0:1]
	v_lshl_add_u64 v[0:1], v[4:5], 0, v[0:1]
	global_load_dwordx4 v[12:15], v[0:1], off
	v_mov_b32_e32 v1, s43
	v_or_b32_e32 v0, s42, v88
	v_lshlrev_b64 v[0:1], 11, v[0:1]
	v_lshl_add_u64 v[0:1], v[4:5], 0, v[0:1]
	global_load_dwordx4 v[16:19], v[0:1], off
	v_mad_i64_i32 v[0:1], s[4:5], s7, v130, v[90:91]
	v_lshlrev_b64 v[0:1], 11, v[0:1]
	v_lshl_add_u64 v[0:1], v[4:5], 0, v[0:1]
	global_load_dwordx4 v[20:23], v[0:1], off
	s_lshl_b64 s[4:5], s[0:1], 6
	v_or_b32_e32 v0, s4, v156
	v_mad_u64_u32 v[0:1], s[24:25], v0, s41, v[84:85]
	v_mad_i32_i24 v1, s5, v132, v1
	global_load_dwordx4 v[24:27], v[0:1], off
	v_or_b32_e32 v0, s4, v92
	v_mad_u64_u32 v[0:1], s[24:25], v0, s41, v[84:85]
	v_mad_i32_i24 v1, s5, v132, v1
	global_load_dwordx4 v[28:31], v[0:1], off
	v_or_b32_e32 v0, s4, v94
	v_mad_u64_u32 v[0:1], s[24:25], v0, s41, v[84:85]
	v_mad_i32_i24 v1, s5, v132, v1
	global_load_dwordx4 v[32:35], v[0:1], off
	v_lshl_add_u64 v[0:1], s[4:5], 0, v[96:97]
	v_mad_u64_u32 v[2:3], s[4:5], v0, s41, v[84:85]
	v_mad_i32_i24 v3, v1, s41, v3
	global_load_dwordx4 v[36:39], v[2:3], off
	s_waitcnt vmcnt(7)
	ds_write_b128 v127, v[8:11]
	s_waitcnt vmcnt(6)
	ds_write_b128 v128, v[12:15]
	s_waitcnt vmcnt(5)
	ds_write_b128 v129, v[16:19]
	s_waitcnt vmcnt(4)
	ds_write_b128 v131, v[20:23]
	s_waitcnt vmcnt(3)
	ds_write_b128 v133, v[24:27] offset:36864
	s_waitcnt vmcnt(2)
	ds_write_b128 v134, v[28:31] offset:36864
	s_waitcnt vmcnt(1)
	ds_write_b128 v135, v[32:35] offset:36864
	s_waitcnt vmcnt(0)
	ds_write_b128 v136, v[36:39] offset:36864
	s_and_saveexec_b64 s[4:5], s[8:9]
	s_cbranch_execz .LBB0_1564
	s_mul_i32 s1, s6, 0x1d1
	v_readlane_b32 s16, v254, 7
	v_add_lshl_u32 v0, s1, v146, 2
	v_readlane_b32 s28, v254, 19
	v_readlane_b32 s29, v254, 20
	v_readlane_b32 s17, v254, 8
	v_readlane_b32 s18, v254, 9
	v_readlane_b32 s19, v254, 10
	v_readlane_b32 s20, v254, 11
	v_readlane_b32 s21, v254, 12
	global_load_dword v0, v0, s[28:29]
	v_readlane_b32 s22, v254, 13
	v_readlane_b32 s23, v254, 14
	v_readlane_b32 s24, v254, 15
	v_readlane_b32 s25, v254, 16
	v_readlane_b32 s26, v254, 17
	v_readlane_b32 s27, v254, 18
	v_readlane_b32 s30, v254, 21
	v_readlane_b32 s31, v254, 22
	s_waitcnt vmcnt(0)
	ds_write_b32 v109, v0
